# FFN-norm (fp8 quant) phase: touch next iteration's 4 rows into L2 one iteration ahead
# speedup vs baseline: 1.0055x; 1.0055x over previous
; __device__ void rmsnorm_rows(const float* src, const float* gw, bf16_t* dst, float* copy, unsigned char* dst8 = nullptr) {
;     ...
;   for (int row0 = blockIdx.x * 4 + w; row0 < T_TOK; row0 += stride * 4) {
;     f32x4 v[4][4];
; #pragma unroll
;     for (int rr = 0; rr < 4; ++rr) {
;       const int row = row0 + rr * stride;
;       if (row < T_TOK) {
;         const f32x4* sp = (const f32x4*)(src + (size_t)row * 1024);
; #pragma unroll
;         for (int k = 0; k < 4; ++k) v[rr][k] = sp[lane + 64 * k];
;       }
;     }
.LBB0_877:
	v_ashrrev_i32_e32 v109, 31, v108
	s_waitcnt vmcnt(13)
	v_lshlrev_b64 v[84:85], 12, v[108:109]
	v_lshl_add_u64 v[84:85], v[2:3], 0, v[84:85]
	v_and_b32_e32 v220, 63, v208
	v_lshrrev_b32_e32 v221, 4, v220
	v_and_b32_e32 v222, 15, v220
	v_lshlrev_b32_e32 v221, 11, v221
	v_add_u32_e32 v221, v221, v108
	v_add_u32_e32 v221, 0x2000, v221
	v_mov_b32_e32 v223, 0x4000
	v_cmp_gt_i32_e32 vcc, v223, v221
	s_nop 1
	v_cndmask_b32_e32 v221, v108, v221, vcc
	v_lshlrev_b32_e32 v223, 12, v221
	v_lshl_add_u32 v223, v222, 8, v223
	v_lshlrev_b32_e32 v222, 4, v220
	v_sub_co_u32_e32 v224, vcc, v2, v222
	v_subbrev_co_u32_e32 v225, vcc, 0, v3, vcc
	v_add_co_u32_e32 v224, vcc, v224, v223
	v_addc_co_u32_e32 v225, vcc, 0, v225, vcc
	global_load_dword v220, v[224:225], off
	global_load_dword v221, v[224:225], off offset:128
	global_load_dwordx4 v[96:99], v[84:85], off
	global_load_dwordx4 v[92:95], v[84:85], off offset:1024
	global_load_dwordx4 v[88:91], v[84:85], off offset:2048
	s_nop 0
	global_load_dwordx4 v[84:87], v[84:85], off offset:3072
	v_add_u32_e32 v102, s86, v108
	s_movk_i32 s0, 0x4000
	v_cmp_gt_i32_e64 s[6:7], s0, v102
	s_and_saveexec_b64 s[0:1], s[6:7]
	s_cbranch_execz .LBB0_879
	v_ashrrev_i32_e32 v103, 31, v102
	v_lshlrev_b64 v[68:69], 12, v[102:103]
	v_lshl_add_u64 v[68:69], v[2:3], 0, v[68:69]
	global_load_dwordx4 v[80:83], v[68:69], off
	global_load_dwordx4 v[76:79], v[68:69], off offset:1024
	global_load_dwordx4 v[72:75], v[68:69], off offset:2048
	s_nop 0
	global_load_dwordx4 v[68:71], v[68:69], off offset:3072
